# final stack plus attention-queue dequeue prefetch (next unit's ticket atomic issued in the prompt unit's drain)
# baseline (speedup 1.0000x reference)
_Z8yoco_fwd4Args:
	s_load_dword s75, s[0:1], 0xf0
	s_load_dwordx4 s[36:39], s[0:1], 0xd8
	s_load_dwordx2 s[34:35], s[0:1], 0xe8
	s_add_u32 s10, s0, 0xf0
	s_mov_b32 s33, s2
	s_mov_b32 s101, 0
	s_addc_u32 s11, s1, 0
	s_waitcnt lgkmcnt(0)
	s_and_b32 s2, s75, 7
	s_cmp_lg_u32 s2, 0
	v_writelane_b32 v250, s33, 0
	s_cbranch_scc1 .LBB0_2
	s_ashr_i32 s3, s33, 31
	s_lshr_b32 s3, s3, 29
	s_add_i32 s3, s33, s3
	s_and_b32 s4, s3, -8
	s_ashr_i32 s2, s75, 3
	s_sub_i32 s4, s33, s4
	s_mul_i32 s2, s2, s4
	s_ashr_i32 s3, s3, 3
	s_add_i32 s2, s2, s3
	v_writelane_b32 v250, s2, 0

.LBB0_924:
	s_and_b64 vcc, exec, s[2:3]
	s_cbranch_vccnz .LBB0_930
	s_cmp_eq_u32 s101, 1
	s_cbranch_scc0 .Ldq9_issue
	s_mov_b32 s101, 0
	s_waitcnt vmcnt(0)
	v_mov_b32_e32 v2, v255
	v_mov_b32_e32 v0, 0
	s_mov_b64 s[4:5], 0
	s_branch .LBB0_929
.Ldq9_issue:
	s_mov_b64 s[4:5], exec
	s_mov_b32 s6, 0

.LBB0_1063:
	v_add_f32_e32 v4, v64, v65
	v_add_f32_e32 v4, v66, v4
	v_add_f32_e32 v4, v67, v4
	v_add_f32_e32 v4, v68, v4
	v_add_f32_e32 v4, v69, v4
	v_add_f32_e32 v4, v70, v4
	v_add_f32_e32 v4, v71, v4
	v_add_f32_e32 v4, v72, v4
	v_add_f32_e32 v4, v73, v4
	v_add_f32_e32 v4, v74, v4
	v_add_f32_e32 v4, v75, v4
	v_add_f32_e32 v4, v76, v4
	v_add_f32_e32 v4, v77, v4
	v_add_f32_e32 v4, v78, v4
	v_add_f32_e32 v4, v79, v4
	v_add_f32_e32 v4, v48, v4
	v_add_f32_e32 v4, v49, v4
	v_add_f32_e32 v4, v50, v4
	v_add_f32_e32 v4, v51, v4
	v_add_f32_e32 v4, v52, v4
	v_add_f32_e32 v4, v53, v4
	v_add_f32_e32 v4, v54, v4
	v_add_f32_e32 v4, v55, v4
	v_add_f32_e32 v4, v56, v4
	v_add_f32_e32 v4, v57, v4
	v_add_f32_e32 v4, v58, v4
	v_add_f32_e32 v4, v59, v4
	v_add_f32_e32 v4, v60, v4
	s_cmp_lg_u32 0, -1
	v_add_f32_e32 v4, v61, v4
	s_cselect_b32 s4, 0, 0
	v_add_f32_e32 v4, v62, v4
	s_addk_i32 s4, 0x6000
	v_add_f32_e32 v4, v63, v4
	v_add3_u32 v3, v212, s4, v209
	v_add_f32_e32 v0, v0, v4
	v_cvt_pk_bf16_f32 v4, v64, v65
	v_cvt_pk_bf16_f32 v5, v66, v67
	v_cvt_pk_bf16_f32 v6, v68, v69
	v_cvt_pk_bf16_f32 v7, v70, v71
	v_cvt_pk_bf16_f32 v8, v72, v73
	v_cvt_pk_bf16_f32 v9, v74, v75
	v_cvt_pk_bf16_f32 v10, v76, v77
	v_cvt_pk_bf16_f32 v11, v78, v79
	v_cvt_pk_bf16_f32 v12, v48, v49
	v_cvt_pk_bf16_f32 v13, v50, v51
	v_cvt_pk_bf16_f32 v14, v52, v53
	v_cvt_pk_bf16_f32 v15, v54, v55
	v_cvt_pk_bf16_f32 v48, v56, v57
	v_cvt_pk_bf16_f32 v49, v58, v59
	v_cvt_pk_bf16_f32 v50, v60, v61
	v_cvt_pk_bf16_f32 v51, v62, v63
	s_cmp_lg_u64 s[2:3], 0
	s_cbranch_scc1 .Ldq9_nopf
	v_mov_b32_e32 v254, 0
	v_mov_b32_e32 v253, 1
	s_mov_b64 s[98:99], exec
	s_mov_b64 exec, 1
	global_atomic_add v255, v254, v253, s[38:39] sc0
	s_mov_b64 exec, s[98:99]
	s_mov_b32 s101, 1
.Ldq9_nopf:
	v_add3_u32 v3, v3, v210, s89
	ds_read_b64_tr_b16 v[52:53],v3 offset:0
	ds_read_b64_tr_b16 v[54:55],v3 offset:512
	ds_read_b64_tr_b16 v[56:57],v3 offset:1024
	ds_read_b64_tr_b16 v[58:59],v3 offset:1536
	ds_read_b64_tr_b16 v[60:61],v3 offset:2048
	ds_read_b64_tr_b16 v[62:63],v3 offset:2560
	ds_read_b64_tr_b16 v[64:65],v3 offset:3072
	ds_read_b64_tr_b16 v[66:67],v3 offset:3584
	s_waitcnt lgkmcnt(0)
	s_nop 0
	v_mfma_f32_32x32x16_bf16 v[32:47], v[4:7], v[52:55], v[32:47]
	ds_read_b64_tr_b16 v[52:53],v3 offset:4096
	ds_read_b64_tr_b16 v[54:55],v3 offset:4608
	v_mfma_f32_32x32x16_bf16 v[32:47], v[8:11], v[56:59], v[32:47]
	ds_read_b64_tr_b16 v[56:57],v3 offset:5120
	ds_read_b64_tr_b16 v[58:59],v3 offset:5632
	v_mfma_f32_32x32x16_bf16 v[32:47], v[12:15], v[60:63], v[32:47]
	ds_read_b64_tr_b16 v[60:61],v3 offset:6144
	ds_read_b64_tr_b16 v[62:63],v3 offset:6656
	ds_read_b64_tr_b16 v[68:69],v3 offset:7168
	ds_read_b64_tr_b16 v[70:71],v3 offset:7680
	s_waitcnt lgkmcnt(0)
	v_mfma_f32_32x32x16_bf16 v[32:47], v[48:51], v[64:67], v[32:47]
	v_mfma_f32_32x32x16_bf16 v[16:31], v[4:7], v[52:55], v[16:31]
	v_mov_b32_e32 v3, v0
	s_nop 1
	v_permlane32_swap_b32_e32 v0, v3
	v_cmp_gt_u32_e32 vcc, 32, v205
	v_mfma_f32_32x32x16_bf16 v[16:31], v[8:11], v[56:59], v[16:31]
	v_mfma_f32_32x32x16_bf16 v[16:31], v[12:15], v[60:63], v[16:31]
	v_mfma_f32_32x32x16_bf16 v[16:31], v[48:51], v[68:71], v[16:31]
	s_and_saveexec_b64 s[4:5], vcc
	v_add_f32_e32 v0, v0, v3
	ds_write_b32 v213, v0 offset:49280
	s_or_b64 exec, exec, s[4:5]
	s_waitcnt lgkmcnt(0)
	ds_read_b128 v[4:7], v2 offset:49280
	ds_read_b128 v[8:11], v2 offset:49312
	s_lshl_b32 s4, s83, 12
	s_add_i32 s4, s4, 0
	v_lshlrev_b32_e32 v50, 9, v208
	s_waitcnt lgkmcnt(1)
	v_rcp_f32_e32 v0, v4
	v_rcp_f32_e32 v3, v5
	v_rcp_f32_e32 v12, v6
	v_rcp_f32_e32 v13, v7
	s_waitcnt lgkmcnt(0)
	v_rcp_f32_e32 v14, v8
	ds_read_b128 v[4:7], v2 offset:49344
	v_rcp_f32_e32 v15, v9
	v_rcp_f32_e32 v48, v10
	v_rcp_f32_e32 v49, v11
	ds_read_b128 v[8:11], v2 offset:49376
	s_waitcnt lgkmcnt(1)
	v_rcp_f32_e32 v2, v4
	v_rcp_f32_e32 v4, v5
	v_rcp_f32_e32 v5, v6
	v_rcp_f32_e32 v6, v7
	s_waitcnt lgkmcnt(0)
	v_rcp_f32_e32 v7, v8
	v_rcp_f32_e32 v8, v9
	v_rcp_f32_e32 v9, v10
	v_rcp_f32_e32 v10, v11
	v_lshlrev_b32_e32 v11, 1, v207
	v_mul_f32_e32 v32, v32, v0
	v_mul_f32_e32 v0, v16, v0
	v_add3_u32 v11, s4, v11, v50
	v_cvt_pk_bf16_f32 v0, v0, s0
	ds_write_b16 v11, v0 offset:51264
	v_mul_f32_e32 v0, v33, v3
	v_cvt_pk_bf16_f32 v0, v0, s0
	ds_write_b16 v11, v0 offset:51328
	v_mul_f32_e32 v0, v17, v3
	v_cvt_pk_bf16_f32 v0, v0, s0
	ds_write_b16 v11, v0 offset:51392
	v_mul_f32_e32 v0, v34, v12
	v_cvt_pk_bf16_f32 v0, v0, s0
	ds_write_b16 v11, v0 offset:51456
	v_mul_f32_e32 v0, v18, v12
	v_cvt_pk_bf16_f32 v0, v0, s0
	ds_write_b16 v11, v0 offset:51520
	v_mul_f32_e32 v0, v35, v13
	v_cvt_pk_bf16_f32 v0, v0, s0
	ds_write_b16 v11, v0 offset:51584
	v_mul_f32_e32 v0, v19, v13
	v_cvt_pk_bf16_f32 v0, v0, s0
	ds_write_b16 v11, v0 offset:51648
	v_mul_f32_e32 v0, v36, v14
	v_cvt_pk_bf16_f32 v0, v0, s0
	ds_write_b16 v11, v0 offset:52224
	v_mul_f32_e32 v0, v20, v14
	v_cvt_pk_bf16_f32 v0, v0, s0
	ds_write_b16 v11, v0 offset:52288
	v_mul_f32_e32 v0, v37, v15
	v_cvt_pk_bf16_f32 v0, v0, s0
	ds_write_b16 v11, v0 offset:52352
	v_mul_f32_e32 v0, v21, v15
	v_cvt_pk_bf16_f32 v0, v0, s0
	ds_write_b16 v11, v0 offset:52416
	v_mul_f32_e32 v0, v38, v48
	v_cvt_pk_bf16_f32 v0, v0, s0
	ds_write_b16 v11, v0 offset:52480
	v_mul_f32_e32 v0, v22, v48
	v_cvt_pk_bf16_f32 v0, v0, s0
	ds_write_b16 v11, v0 offset:52544
	v_mul_f32_e32 v0, v39, v49
	v_cvt_pk_bf16_f32 v0, v0, s0
	ds_write_b16 v11, v0 offset:52608
	v_mul_f32_e32 v0, v23, v49
	v_cvt_pk_bf16_f32 v0, v0, s0
	ds_write_b16 v11, v0 offset:52672
	v_mul_f32_e32 v0, v40, v2
	v_cvt_pk_bf16_f32 v0, v0, s0
	ds_write_b16 v11, v0 offset:53248
	v_mul_f32_e32 v0, v24, v2
	v_cvt_pk_bf16_f32 v0, v0, s0
	ds_write_b16 v11, v0 offset:53312
	v_mul_f32_e32 v0, v41, v4
	v_cvt_pk_bf16_f32 v0, v0, s0
	ds_write_b16 v11, v0 offset:53376
	v_mul_f32_e32 v0, v25, v4
	v_cvt_pk_bf16_f32 v0, v0, s0
	ds_write_b16 v11, v0 offset:53440
	v_mul_f32_e32 v0, v42, v5
	v_cvt_pk_bf16_f32 v0, v0, s0
	ds_write_b16 v11, v0 offset:53504
	v_mul_f32_e32 v0, v26, v5
	v_cvt_pk_bf16_f32 v0, v0, s0
	ds_write_b16 v11, v0 offset:53568
	v_mul_f32_e32 v0, v43, v6
	v_cvt_pk_bf16_f32 v0, v0, s0
	ds_write_b16 v11, v0 offset:53632
	v_mul_f32_e32 v0, v27, v6
	v_cvt_pk_bf16_f32 v0, v0, s0
	ds_write_b16 v11, v0 offset:53696
	v_mul_f32_e32 v0, v44, v7
	v_cvt_pk_bf16_f32 v0, v0, s0
	ds_write_b16 v11, v0 offset:54272
	v_mul_f32_e32 v0, v28, v7
	v_cvt_pk_bf16_f32 v0, v0, s0
	ds_write_b16 v11, v0 offset:54336
	v_mul_f32_e32 v0, v45, v8
	v_cvt_pk_bf16_f32 v0, v0, s0
	ds_write_b16 v11, v0 offset:54400
	v_mul_f32_e32 v0, v29, v8
	v_cvt_pk_bf16_f32 v0, v0, s0
	ds_write_b16 v11, v0 offset:54464
	v_mul_f32_e32 v0, v46, v9
	v_cvt_pk_bf16_f32 v0, v0, s0
	ds_write_b16 v11, v0 offset:54528
	v_mul_f32_e32 v0, v30, v9
	v_cvt_pk_bf16_f32 v0, v0, s0
	ds_write_b16 v11, v0 offset:54592
	v_mul_f32_e32 v0, v47, v10
	v_cvt_pk_bf16_f32 v0, v0, s0
	ds_write_b16 v11, v0 offset:54656
	v_mul_f32_e32 v0, v31, v10
	v_cvt_pk_bf16_f32 v0, v0, s0
	ds_write_b16 v11, v0 offset:54720
	v_lshlrev_b32_e32 v0, 1, v206
	v_cvt_pk_bf16_f32 v32, v32, s0
	v_and_b32_e32 v0, 0x70, v0
	ds_write_b16 v11, v32 offset:51200
	v_lshrrev_b32_e32 v14, 3, v205
	v_add_u32_e32 v15, s4, v0
	s_waitcnt lgkmcnt(0)
	v_lshl_add_u64 v[10:11], s[30:31], 0, v[0:1]
	v_lshl_add_u32 v0, v14, 7, v15
	v_or_b32_e32 v16, 8, v14
	ds_read_b128 v[2:5], v0 offset:51200
	v_lshl_add_u32 v6, v16, 7, v15
	ds_read_b128 v[6:9], v6 offset:51200
	v_lshlrev_b32_e32 v0, 11, v14
	v_lshl_add_u64 v[12:13], v[10:11], 0, v[0:1]
	v_lshlrev_b32_e32 v0, 11, v16
	s_waitcnt lgkmcnt(1)
	global_store_dwordx4 v[12:13], v[2:5], off
	s_nop 1
	v_lshl_add_u64 v[2:3], v[10:11], 0, v[0:1]
	v_or_b32_e32 v0, 16, v14
	s_waitcnt lgkmcnt(0)
	global_store_dwordx4 v[2:3], v[6:9], off
	v_lshl_add_u32 v2, v0, 7, v15
	v_or_b32_e32 v14, 24, v14
	ds_read_b128 v[2:5], v2 offset:51200
	v_lshl_add_u32 v6, v14, 7, v15
	ds_read_b128 v[6:9], v6 offset:51200
	v_lshlrev_b32_e32 v0, 11, v0
	v_lshl_add_u64 v[12:13], v[10:11], 0, v[0:1]
	v_lshlrev_b32_e32 v0, 11, v14
	s_waitcnt lgkmcnt(1)
	global_store_dwordx4 v[12:13], v[2:5], off
	s_nop 1
	v_lshl_add_u64 v[2:3], v[10:11], 0, v[0:1]
	s_waitcnt lgkmcnt(0)
	global_store_dwordx4 v[2:3], v[6:9], off
	s_waitcnt lgkmcnt(0)
	s_barrier
	s_and_b64 vcc, exec, s[28:29]
	s_cbranch_vccz .LBB0_922
